# MLP-up GEMM epilogue: next row's sum-of-squares loads prefetched into dead fragment registers, waits no longer cover stores
# baseline (speedup 1.0000x reference)
; DEVI unsigned pk2(float lo, float hi) { unsigned r; asm("v_cvt_pk_bf16_f32 %0, %1, %2" : "=v"(r) : "v"(lo), "v"(hi)); return r; }
;   DEVI void operator()(const f32x4 (&acc)[2][2][4][2], const pg8::Unit& u, int wr, int wc, int fr, int fq) const {
;     ...
;       for (int m = 0; m < 4; ++m) {
;         const int row = u.pm * 256 + ai * 128 + wr * 64 + m * 16 + fr;
;         const float4* sp = (const float4*)(ssrow + (size_t)row * 16);
;         const float4 a = sp[0], b = sp[1], c = sp[2], d = sp[3];
;         const float ssum = (((a.x + a.y) + (a.z + a.w)) + ((b.x + b.y) + (b.z + b.w))) + (((c.x + c.y) + (c.z + c.w)) + ((d.x + d.y) + (d.z + d.w)));
;         const float rs = rsqrtf(ssum * (1.f / 1024.f) + 1e-6f);
; #pragma unroll
;         for (int bj = 0; bj < 2; ++bj) {
;           const int col = u.pn * 256 + bj * 128 + wc * 32 + fq * 8;
;           float h[8];
; #pragma unroll
;           for (int j = 0; j < 4; ++j) { const float h0 = fmaxf(acc[ai][bj][m][0][j] * rs, 0.f), h1 = fmaxf(acc[ai][bj][m][1][j] * rs, 0.f); h[j] = h0 * h0; h[4 + j] = h1 * h1; }
;           u32x4 w; w.x = pk2(h[0], h[1]); w.y = pk2(h[2], h[3]); w.z = pk2(h[4], h[5]); w.w = pk2(h[6], h[7]);
;           *(u32x4*)(uo + (size_t)row * DFF + col) = w;
;         }
.LBB0_1974:
	v_lshl_add_u32 v146, s3, 8, v131
	v_ashrrev_i32_e32 v147, 31, v146
	v_lshlrev_b64 v[132:133], 6, v[146:147]
	v_lshl_add_u64 v[162:163], s[54:55], 0, v[132:133]
	v_mov_b32_e32 v200, v162
	v_mov_b32_e32 v201, v163
	v_add_u32_e32 v204, 0x80, v146
	v_ashrrev_i32_e32 v205, 31, v204
	v_lshlrev_b64 v[202:203], 6, v[204:205]
	v_lshl_add_u64 v[202:203], s[54:55], 0, v[202:203]
	global_load_dwordx4 v[132:135], v[162:163], off offset:48
	global_load_dwordx4 v[154:157], v[162:163], off offset:16
	global_load_dwordx4 v[158:161], v[162:163], off offset:32
	s_nop 0
	global_load_dwordx4 v[162:165], v[162:163], off
	v_lshl_or_b32 v148, s2, 8, v151
	v_readlane_b32 s24, v252, 40
	v_readlane_b32 s26, v252, 42
	v_readlane_b32 s27, v252, 43
	v_ashrrev_i32_e32 v149, 31, v148
	s_mov_b64 s[22:23], -1
	v_readlane_b32 s25, v252, 41
	s_waitcnt vmcnt(0)
	global_load_dwordx4 v[168:171], v[200:201], off offset:1072
	global_load_dwordx4 v[172:175], v[200:201], off offset:1040
	global_load_dwordx4 v[176:179], v[200:201], off offset:1056
	global_load_dwordx4 v[180:183], v[200:201], off offset:1024
	v_mov_b32_e32 v167, v158
	v_mov_b32_e32 v166, v162
	v_mov_b32_e32 v158, v163
	v_mov_b32_e32 v162, v164
	v_mov_b32_e32 v163, v160
	v_mov_b32_e32 v160, v165
	v_pk_add_f32 v[158:159], v[166:167], v[158:159]
	v_pk_add_f32 v[160:161], v[162:163], v[160:161]
	s_nop 0
	v_pk_add_f32 v[158:159], v[158:159], v[160:161]
	v_mov_b32_e32 v160, v154
	v_mov_b32_e32 v161, v132
	v_mov_b32_e32 v132, v155
	v_mov_b32_e32 v154, v156
	v_mov_b32_e32 v155, v134
	v_mov_b32_e32 v134, v157
	v_pk_add_f32 v[132:133], v[160:161], v[132:133]
	v_pk_add_f32 v[134:135], v[154:155], v[134:135]
	s_nop 0
	v_pk_add_f32 v[132:133], v[132:133], v[134:135]
	s_nop 0
	v_pk_add_f32 v[132:133], v[158:159], v[132:133]
	s_nop 0
	v_add_f32_e32 v132, v132, v133
	v_fmamk_f32 v132, v132, 0x3a800000, v224
	v_cmp_gt_f32_e32 vcc, s77, v132
	v_mul_f32_e32 v133, 0x4b800000, v132
	s_nop 0
	v_cndmask_b32_e32 v132, v132, v133, vcc
	v_rsq_f32_e32 v132, v132
	s_nop 0
	v_mul_f32_e32 v133, 0x45800000, v132
	v_cndmask_b32_e32 v134, v132, v133, vcc
	v_mul_f32_e32 v122, v122, v134
	v_mul_f32_e32 v123, v123, v134
	v_mul_f32_e32 v124, v124, v134
	v_max_f32_e32 v122, 0, v122
	v_max_f32_e32 v123, 0, v123
	v_max_f32_e32 v124, 0, v124
	v_mul_f32_e32 v126, v126, v134
	v_mul_f32_e32 v135, v122, v122
	v_mul_f32_e32 v122, v127, v134
	v_mul_f32_e32 v127, v123, v123
	v_mul_f32_e32 v123, v128, v134
	v_mul_f32_e32 v128, v124, v124
	v_mul_f32_e32 v124, v129, v134
	v_mul_f32_e32 v125, v125, v134
	v_max_f32_e32 v126, 0, v126
	v_max_f32_e32 v122, 0, v122
	v_max_f32_e32 v123, 0, v123
	v_max_f32_e32 v124, 0, v124
	v_max_f32_e32 v125, 0, v125
	v_lshlrev_b64 v[132:133], 13, v[146:147]
	v_mul_f32_e32 v126, v126, v126
	v_mul_f32_e32 v122, v122, v122
	v_mul_f32_e32 v123, v123, v123
	v_mul_f32_e32 v124, v124, v124
	v_mul_f32_e32 v125, v125, v125
	v_cvt_pk_bf16_f32 v122, v126, v122
	v_cvt_pk_bf16_f32 v123, v123, v124
	v_cvt_pk_bf16_f32 v124, v135, v127
	v_cvt_pk_bf16_f32 v125, v128, v125
	v_lshl_add_u64 v[128:129], s[26:27], 0, v[132:133]
	v_lshlrev_b64 v[126:127], 1, v[148:149]
	v_mul_f32_e32 v114, v114, v134
	v_mul_f32_e32 v115, v115, v134
	v_mul_f32_e32 v116, v116, v134
	v_lshl_add_u64 v[128:129], v[128:129], 0, v[126:127]
	v_max_f32_e32 v114, 0, v114
	v_max_f32_e32 v115, 0, v115
	v_max_f32_e32 v116, 0, v116
	global_store_dwordx4 v[128:129], v[122:125], off
	v_mul_f32_e32 v117, v117, v134
	v_mul_f32_e32 v118, v118, v134
	v_mul_f32_e32 v122, v114, v114
	v_mul_f32_e32 v114, v119, v134
	v_mul_f32_e32 v119, v115, v115
	v_mul_f32_e32 v115, v120, v134
	v_mul_f32_e32 v120, v116, v116
	v_mul_f32_e32 v116, v121, v134
	v_max_f32_e32 v114, 0, v114
	v_max_f32_e32 v115, 0, v115
	v_max_f32_e32 v116, 0, v116
	v_max_f32_e32 v117, 0, v117
	v_max_f32_e32 v118, 0, v118
	v_mul_f32_e32 v114, v114, v114
	v_mul_f32_e32 v115, v115, v115
	v_mul_f32_e32 v116, v116, v116
	v_mul_f32_e32 v117, v117, v117
	v_mul_f32_e32 v118, v118, v118
	v_cvt_pk_bf16_f32 v114, v118, v114
	v_cvt_pk_bf16_f32 v115, v115, v116
	v_cvt_pk_bf16_f32 v116, v122, v119
	v_cvt_pk_bf16_f32 v117, v120, v117
	global_store_dwordx4 v[128:129], v[114:117], off offset:256
	v_or_b32_e32 v128, 16, v146
	v_ashrrev_i32_e32 v129, 31, v128
	v_lshlrev_b64 v[114:115], 6, v[128:129]
	v_lshl_add_u64 v[148:149], s[54:55], 0, v[114:115]
	s_waitcnt vmcnt(2)
; DEVI unsigned pk2(float lo, float hi) { unsigned r; asm("v_cvt_pk_bf16_f32 %0, %1, %2" : "=v"(r) : "v"(lo), "v"(hi)); return r; }
;   DEVI void operator()(const f32x4 (&acc)[2][2][4][2], const pg8::Unit& u, int wr, int wc, int fr, int fq) const {
;     ...
;       for (int m = 0; m < 4; ++m) {
;         const int row = u.pm * 256 + ai * 128 + wr * 64 + m * 16 + fr;
;         const float4* sp = (const float4*)(ssrow + (size_t)row * 16);
;         const float4 a = sp[0], b = sp[1], c = sp[2], d = sp[3];
;         const float ssum = (((a.x + a.y) + (a.z + a.w)) + ((b.x + b.y) + (b.z + b.w))) + (((c.x + c.y) + (c.z + c.w)) + ((d.x + d.y) + (d.z + d.w)));
;         const float rs = rsqrtf(ssum * (1.f / 1024.f) + 1e-6f);
; #pragma unroll
;         for (int bj = 0; bj < 2; ++bj) {
;           const int col = u.pn * 256 + bj * 128 + wc * 32 + fq * 8;
;           float h[8];
; #pragma unroll
;           for (int j = 0; j < 4; ++j) { const float h0 = fmaxf(acc[ai][bj][m][0][j] * rs, 0.f), h1 = fmaxf(acc[ai][bj][m][1][j] * rs, 0.f); h[j] = h0 * h0; h[4 + j] = h1 * h1; }
;           u32x4 w; w.x = pk2(h[0], h[1]); w.y = pk2(h[2], h[3]); w.z = pk2(h[4], h[5]); w.w = pk2(h[6], h[7]);
;           *(u32x4*)(uo + (size_t)row * DFF + col) = w;
;         }
	v_mov_b32_e32 v114, v168
	v_mov_b32_e32 v115, v169
	v_mov_b32_e32 v116, v170
	v_mov_b32_e32 v117, v171
	v_mov_b32_e32 v118, v172
	v_mov_b32_e32 v119, v173
	v_mov_b32_e32 v120, v174
	v_mov_b32_e32 v121, v175
	v_mov_b32_e32 v122, v176
	v_mov_b32_e32 v123, v177
	v_mov_b32_e32 v124, v178
	v_mov_b32_e32 v125, v179
	v_mov_b32_e32 v132, v180
	v_mov_b32_e32 v133, v181
	v_mov_b32_e32 v134, v182
	v_mov_b32_e32 v135, v183
	global_load_dwordx4 v[184:187], v[200:201], off offset:2096
	global_load_dwordx4 v[188:191], v[200:201], off offset:2064
	global_load_dwordx4 v[192:195], v[200:201], off offset:2080
	global_load_dwordx4 v[196:199], v[200:201], off offset:2048
	v_mov_b32_e32 v149, v122
	v_mov_b32_e32 v148, v132
	v_mov_b32_e32 v122, v133
	v_mov_b32_e32 v132, v134
	v_mov_b32_e32 v133, v124
	v_mov_b32_e32 v124, v135
	v_pk_add_f32 v[122:123], v[148:149], v[122:123]
	v_pk_add_f32 v[124:125], v[132:133], v[124:125]
	s_nop 0
	v_pk_add_f32 v[122:123], v[122:123], v[124:125]
	v_mov_b32_e32 v124, v118
	v_mov_b32_e32 v125, v114
	v_mov_b32_e32 v114, v119
	v_mov_b32_e32 v118, v120
	v_mov_b32_e32 v119, v116
	v_mov_b32_e32 v116, v121
	v_pk_add_f32 v[114:115], v[124:125], v[114:115]
	v_pk_add_f32 v[116:117], v[118:119], v[116:117]
	s_nop 0
	v_pk_add_f32 v[114:115], v[114:115], v[116:117]
	s_nop 0
	v_pk_add_f32 v[114:115], v[122:123], v[114:115]
	s_nop 0
	v_add_f32_e32 v114, v114, v115
	v_fmamk_f32 v114, v114, 0x3a800000, v224
	v_cmp_gt_f32_e32 vcc, s77, v114
	v_mul_f32_e32 v115, 0x4b800000, v114
	s_nop 0
	v_cndmask_b32_e32 v114, v114, v115, vcc
	v_rsq_f32_e32 v114, v114
	s_nop 0
	v_mul_f32_e32 v115, 0x45800000, v114
	v_cndmask_b32_e32 v116, v114, v115, vcc
	v_mul_f32_e32 v106, v106, v116
	v_mul_f32_e32 v107, v107, v116
	v_mul_f32_e32 v108, v108, v116
	v_max_f32_e32 v106, 0, v106
	v_max_f32_e32 v107, 0, v107
	v_max_f32_e32 v108, 0, v108
	v_mul_f32_e32 v110, v110, v116
	v_mul_f32_e32 v117, v106, v106
	v_mul_f32_e32 v106, v111, v116
	v_mul_f32_e32 v111, v107, v107
	v_mul_f32_e32 v107, v112, v116
	v_mul_f32_e32 v112, v108, v108
	v_mul_f32_e32 v108, v113, v116
	v_max_f32_e32 v110, 0, v110
	v_max_f32_e32 v106, 0, v106
	v_max_f32_e32 v107, 0, v107
	v_max_f32_e32 v108, 0, v108
	v_lshlrev_b64 v[114:115], 13, v[128:129]
	v_mul_f32_e32 v110, v110, v110
	v_mul_f32_e32 v106, v106, v106
	v_mul_f32_e32 v107, v107, v107
	v_mul_f32_e32 v109, v109, v116
	v_mul_f32_e32 v108, v108, v108
	v_max_f32_e32 v109, 0, v109
	v_cvt_pk_bf16_f32 v106, v110, v106
	v_cvt_pk_bf16_f32 v107, v107, v108
	v_cvt_pk_bf16_f32 v108, v117, v111
	v_lshl_add_u64 v[110:111], s[26:27], 0, v[114:115]
	v_mul_f32_e32 v98, v98, v116
	v_mul_f32_e32 v99, v99, v116
	v_mul_f32_e32 v100, v100, v116
	v_mul_f32_e32 v109, v109, v109
	v_lshl_add_u64 v[110:111], v[110:111], 0, v[126:127]
	v_max_f32_e32 v98, 0, v98
	v_max_f32_e32 v99, 0, v99
	v_max_f32_e32 v100, 0, v100
	v_cvt_pk_bf16_f32 v109, v112, v109
	global_store_dwordx4 v[110:111], v[106:109], off
	v_mul_f32_e32 v101, v101, v116
	v_mul_f32_e32 v102, v102, v116
	v_mul_f32_e32 v106, v98, v98
	v_mul_f32_e32 v98, v103, v116
	v_mul_f32_e32 v103, v99, v99
	v_mul_f32_e32 v99, v104, v116
	v_mul_f32_e32 v104, v100, v100
	v_mul_f32_e32 v100, v105, v116
	v_max_f32_e32 v98, 0, v98
	v_max_f32_e32 v99, 0, v99
	v_max_f32_e32 v100, 0, v100
	v_max_f32_e32 v101, 0, v101
	v_max_f32_e32 v102, 0, v102
	v_mul_f32_e32 v98, v98, v98
	v_mul_f32_e32 v99, v99, v99
	v_mul_f32_e32 v100, v100, v100
	v_mul_f32_e32 v101, v101, v101
	v_mul_f32_e32 v102, v102, v102
	v_cvt_pk_bf16_f32 v98, v102, v98
	v_cvt_pk_bf16_f32 v99, v99, v100
	v_cvt_pk_bf16_f32 v100, v106, v103
	v_cvt_pk_bf16_f32 v101, v104, v101
	global_store_dwordx4 v[110:111], v[98:101], off offset:256
	v_or_b32_e32 v110, 32, v146
	v_ashrrev_i32_e32 v111, 31, v110
	v_lshlrev_b64 v[98:99], 6, v[110:111]
	v_lshl_add_u64 v[112:113], s[54:55], 0, v[98:99]
	s_waitcnt vmcnt(2)
	v_mov_b32_e32 v98, v184
	v_mov_b32_e32 v99, v185
	v_mov_b32_e32 v100, v186
	v_mov_b32_e32 v101, v187
	v_mov_b32_e32 v102, v188
	v_mov_b32_e32 v103, v189
	v_mov_b32_e32 v104, v190
	v_mov_b32_e32 v105, v191
	v_mov_b32_e32 v106, v192
	v_mov_b32_e32 v107, v193
	v_mov_b32_e32 v108, v194
	v_mov_b32_e32 v109, v195
	v_mov_b32_e32 v112, v196
	v_mov_b32_e32 v113, v197
	v_mov_b32_e32 v114, v198
	v_mov_b32_e32 v115, v199
	global_load_dwordx4 v[168:171], v[200:201], off offset:3120
	global_load_dwordx4 v[172:175], v[200:201], off offset:3088
	global_load_dwordx4 v[176:179], v[200:201], off offset:3104
	global_load_dwordx4 v[180:183], v[200:201], off offset:3072
	v_mov_b32_e32 v117, v106
	v_mov_b32_e32 v116, v112
	v_mov_b32_e32 v106, v113
	v_mov_b32_e32 v112, v114
	v_mov_b32_e32 v113, v108
	v_mov_b32_e32 v108, v115
	v_pk_add_f32 v[106:107], v[116:117], v[106:107]
	v_pk_add_f32 v[108:109], v[112:113], v[108:109]
	s_nop 0
	v_pk_add_f32 v[106:107], v[106:107], v[108:109]
	v_mov_b32_e32 v108, v102
	v_mov_b32_e32 v109, v98
	v_mov_b32_e32 v98, v103
	v_mov_b32_e32 v102, v104
	v_mov_b32_e32 v103, v100
	v_mov_b32_e32 v100, v105
	v_pk_add_f32 v[98:99], v[108:109], v[98:99]
	v_pk_add_f32 v[100:101], v[102:103], v[100:101]
	s_nop 0
	v_pk_add_f32 v[98:99], v[98:99], v[100:101]
	s_nop 0
	v_pk_add_f32 v[98:99], v[106:107], v[98:99]
	s_nop 0
	v_add_f32_e32 v98, v98, v99
	v_fmamk_f32 v98, v98, 0x3a800000, v224
	v_cmp_gt_f32_e32 vcc, s77, v98
	v_mul_f32_e32 v99, 0x4b800000, v98
	s_nop 0
	v_cndmask_b32_e32 v98, v98, v99, vcc
	v_rsq_f32_e32 v98, v98
	s_nop 0
	v_mul_f32_e32 v99, 0x45800000, v98
	v_cndmask_b32_e32 v100, v98, v99, vcc
	v_mul_f32_e32 v90, v90, v100
	v_mul_f32_e32 v91, v91, v100
	v_mul_f32_e32 v92, v92, v100
	v_max_f32_e32 v90, 0, v90
	v_max_f32_e32 v91, 0, v91
	v_max_f32_e32 v92, 0, v92
; DEVI unsigned pk2(float lo, float hi) { unsigned r; asm("v_cvt_pk_bf16_f32 %0, %1, %2" : "=v"(r) : "v"(lo), "v"(hi)); return r; }
;   DEVI void operator()(const f32x4 (&acc)[2][2][4][2], const pg8::Unit& u, int wr, int wc, int fr, int fq) const {
;     ...
;       for (int m = 0; m < 4; ++m) {
;         const int row = u.pm * 256 + ai * 128 + wr * 64 + m * 16 + fr;
;         const float4* sp = (const float4*)(ssrow + (size_t)row * 16);
;         const float4 a = sp[0], b = sp[1], c = sp[2], d = sp[3];
;         const float ssum = (((a.x + a.y) + (a.z + a.w)) + ((b.x + b.y) + (b.z + b.w))) + (((c.x + c.y) + (c.z + c.w)) + ((d.x + d.y) + (d.z + d.w)));
;         const float rs = rsqrtf(ssum * (1.f / 1024.f) + 1e-6f);
; #pragma unroll
;         for (int bj = 0; bj < 2; ++bj) {
;           const int col = u.pn * 256 + bj * 128 + wc * 32 + fq * 8;
;           float h[8];
; #pragma unroll
;           for (int j = 0; j < 4; ++j) { const float h0 = fmaxf(acc[ai][bj][m][0][j] * rs, 0.f), h1 = fmaxf(acc[ai][bj][m][1][j] * rs, 0.f); h[j] = h0 * h0; h[4 + j] = h1 * h1; }
;           u32x4 w; w.x = pk2(h[0], h[1]); w.y = pk2(h[2], h[3]); w.z = pk2(h[4], h[5]); w.w = pk2(h[6], h[7]);
;           *(u32x4*)(uo + (size_t)row * DFF + col) = w;
;         }
	v_mul_f32_e32 v94, v94, v100
	v_mul_f32_e32 v101, v90, v90
	v_mul_f32_e32 v90, v95, v100
	v_mul_f32_e32 v95, v91, v91
	v_mul_f32_e32 v91, v96, v100
	v_mul_f32_e32 v96, v92, v92
	v_mul_f32_e32 v92, v97, v100
	v_max_f32_e32 v94, 0, v94
	v_max_f32_e32 v90, 0, v90
	v_max_f32_e32 v91, 0, v91
	v_max_f32_e32 v92, 0, v92
	v_lshlrev_b64 v[98:99], 13, v[110:111]
	v_mul_f32_e32 v94, v94, v94
	v_mul_f32_e32 v90, v90, v90
	v_mul_f32_e32 v91, v91, v91
	v_mul_f32_e32 v93, v93, v100
	v_mul_f32_e32 v92, v92, v92
	v_max_f32_e32 v93, 0, v93
	v_cvt_pk_bf16_f32 v90, v94, v90
	v_cvt_pk_bf16_f32 v91, v91, v92
	v_cvt_pk_bf16_f32 v92, v101, v95
	v_lshl_add_u64 v[94:95], s[26:27], 0, v[98:99]
	v_mul_f32_e32 v82, v82, v100
	v_mul_f32_e32 v83, v83, v100
	v_mul_f32_e32 v84, v84, v100
	v_mul_f32_e32 v93, v93, v93
	v_lshl_add_u64 v[94:95], v[94:95], 0, v[126:127]
	v_max_f32_e32 v82, 0, v82
	v_max_f32_e32 v83, 0, v83
	v_max_f32_e32 v84, 0, v84
	v_cvt_pk_bf16_f32 v93, v96, v93
	global_store_dwordx4 v[94:95], v[90:93], off
	v_mul_f32_e32 v85, v85, v100
	v_mul_f32_e32 v86, v86, v100
	v_mul_f32_e32 v90, v82, v82
	v_mul_f32_e32 v82, v87, v100
	v_mul_f32_e32 v87, v83, v83
	v_mul_f32_e32 v83, v88, v100
	v_mul_f32_e32 v88, v84, v84
	v_mul_f32_e32 v84, v89, v100
	v_max_f32_e32 v82, 0, v82
	v_max_f32_e32 v83, 0, v83
	v_max_f32_e32 v84, 0, v84
	v_max_f32_e32 v85, 0, v85
	v_max_f32_e32 v86, 0, v86
	v_mul_f32_e32 v82, v82, v82
	v_mul_f32_e32 v83, v83, v83
	v_mul_f32_e32 v84, v84, v84
	v_mul_f32_e32 v85, v85, v85
	v_mul_f32_e32 v86, v86, v86
	v_cvt_pk_bf16_f32 v82, v86, v82
	v_cvt_pk_bf16_f32 v83, v83, v84
	v_cvt_pk_bf16_f32 v84, v90, v87
	v_cvt_pk_bf16_f32 v85, v88, v85
	global_store_dwordx4 v[94:95], v[82:85], off offset:256
	v_or_b32_e32 v94, 48, v146
	v_ashrrev_i32_e32 v95, 31, v94
	v_lshlrev_b64 v[82:83], 6, v[94:95]
	v_lshl_add_u64 v[96:97], s[54:55], 0, v[82:83]
	s_waitcnt vmcnt(2)
	v_mov_b32_e32 v82, v168
	v_mov_b32_e32 v83, v169
	v_mov_b32_e32 v84, v170
	v_mov_b32_e32 v85, v171
	v_mov_b32_e32 v86, v172
	v_mov_b32_e32 v87, v173
	v_mov_b32_e32 v88, v174
	v_mov_b32_e32 v89, v175
	v_mov_b32_e32 v90, v176
	v_mov_b32_e32 v91, v177
	v_mov_b32_e32 v92, v178
	v_mov_b32_e32 v93, v179
	v_mov_b32_e32 v96, v180
	v_mov_b32_e32 v97, v181
	v_mov_b32_e32 v98, v182
	v_mov_b32_e32 v99, v183
	global_load_dwordx4 v[184:187], v[202:203], off offset:48
	global_load_dwordx4 v[188:191], v[202:203], off offset:16
	global_load_dwordx4 v[192:195], v[202:203], off offset:32
	global_load_dwordx4 v[196:199], v[202:203], off offset:0
	v_mov_b32_e32 v101, v90
	v_mov_b32_e32 v100, v96
	v_mov_b32_e32 v90, v97
	v_mov_b32_e32 v96, v98
	v_mov_b32_e32 v97, v92
	v_mov_b32_e32 v92, v99
	v_pk_add_f32 v[90:91], v[100:101], v[90:91]
	v_pk_add_f32 v[92:93], v[96:97], v[92:93]
	s_nop 0
	v_pk_add_f32 v[90:91], v[90:91], v[92:93]
	v_mov_b32_e32 v92, v86
	v_mov_b32_e32 v93, v82
	v_mov_b32_e32 v82, v87
	v_mov_b32_e32 v86, v88
	v_mov_b32_e32 v87, v84
	v_mov_b32_e32 v84, v89
	v_pk_add_f32 v[82:83], v[92:93], v[82:83]
	v_pk_add_f32 v[84:85], v[86:87], v[84:85]
	s_nop 0
	v_pk_add_f32 v[82:83], v[82:83], v[84:85]
	s_nop 0
	v_pk_add_f32 v[82:83], v[90:91], v[82:83]
	s_nop 0
	v_add_f32_e32 v82, v82, v83
	v_fmamk_f32 v82, v82, 0x3a800000, v224
	v_cmp_gt_f32_e32 vcc, s77, v82
	v_mul_f32_e32 v83, 0x4b800000, v82
	s_nop 0
	v_cndmask_b32_e32 v82, v82, v83, vcc
	v_rsq_f32_e32 v82, v82
	s_nop 0
	v_mul_f32_e32 v83, 0x45800000, v82
	v_cndmask_b32_e32 v84, v82, v83, vcc
	v_mul_f32_e32 v74, v74, v84
	v_mul_f32_e32 v75, v75, v84
	v_mul_f32_e32 v76, v76, v84
	v_max_f32_e32 v74, 0, v74
	v_max_f32_e32 v75, 0, v75
	v_max_f32_e32 v76, 0, v76
	v_mul_f32_e32 v78, v78, v84
	v_mul_f32_e32 v85, v74, v74
	v_mul_f32_e32 v74, v79, v84
	v_mul_f32_e32 v79, v75, v75
	v_mul_f32_e32 v75, v80, v84
	v_mul_f32_e32 v80, v76, v76
	v_mul_f32_e32 v76, v81, v84
	v_max_f32_e32 v78, 0, v78
	v_max_f32_e32 v74, 0, v74
	v_max_f32_e32 v75, 0, v75
	v_max_f32_e32 v76, 0, v76
	v_lshlrev_b64 v[82:83], 13, v[94:95]
	v_mul_f32_e32 v78, v78, v78
	v_mul_f32_e32 v74, v74, v74
	v_mul_f32_e32 v75, v75, v75
	v_mul_f32_e32 v77, v77, v84
	v_mul_f32_e32 v76, v76, v76
	v_max_f32_e32 v77, 0, v77
	v_cvt_pk_bf16_f32 v74, v78, v74
	v_cvt_pk_bf16_f32 v75, v75, v76
	v_cvt_pk_bf16_f32 v76, v85, v79
	v_lshl_add_u64 v[78:79], s[26:27], 0, v[82:83]
	v_mul_f32_e32 v66, v66, v84
	v_mul_f32_e32 v67, v67, v84
	v_mul_f32_e32 v68, v68, v84
	v_mul_f32_e32 v77, v77, v77
	v_lshl_add_u64 v[78:79], v[78:79], 0, v[126:127]
	v_max_f32_e32 v66, 0, v66
	v_max_f32_e32 v67, 0, v67
	v_max_f32_e32 v68, 0, v68
	v_cvt_pk_bf16_f32 v77, v80, v77
	global_store_dwordx4 v[78:79], v[74:77], off
	v_mul_f32_e32 v69, v69, v84
	v_mul_f32_e32 v70, v70, v84
	v_mul_f32_e32 v74, v66, v66
	v_mul_f32_e32 v66, v71, v84
	v_mul_f32_e32 v71, v67, v67
	v_mul_f32_e32 v67, v72, v84
	v_mul_f32_e32 v72, v68, v68
	v_mul_f32_e32 v68, v73, v84
	v_max_f32_e32 v66, 0, v66
	v_max_f32_e32 v67, 0, v67
	v_max_f32_e32 v68, 0, v68
	v_max_f32_e32 v69, 0, v69
	v_max_f32_e32 v70, 0, v70
	v_mul_f32_e32 v66, v66, v66
	v_mul_f32_e32 v67, v67, v67
	v_mul_f32_e32 v68, v68, v68
	v_mul_f32_e32 v69, v69, v69
	v_mul_f32_e32 v70, v70, v70
	v_cvt_pk_bf16_f32 v66, v70, v66
	v_cvt_pk_bf16_f32 v67, v67, v68
	v_cvt_pk_bf16_f32 v68, v74, v71
	v_cvt_pk_bf16_f32 v69, v72, v69
	global_store_dwordx4 v[78:79], v[66:69], off offset:256
	v_add_u32_e32 v78, 0x80, v146
	v_ashrrev_i32_e32 v79, 31, v78
	v_lshlrev_b64 v[66:67], 6, v[78:79]
	v_lshl_add_u64 v[80:81], s[54:55], 0, v[66:67]
	s_waitcnt vmcnt(2)
; DEVI unsigned pk2(float lo, float hi) { unsigned r; asm("v_cvt_pk_bf16_f32 %0, %1, %2" : "=v"(r) : "v"(lo), "v"(hi)); return r; }
;   DEVI void operator()(const f32x4 (&acc)[2][2][4][2], const pg8::Unit& u, int wr, int wc, int fr, int fq) const {
;     ...
;       for (int m = 0; m < 4; ++m) {
;         const int row = u.pm * 256 + ai * 128 + wr * 64 + m * 16 + fr;
;         const float4* sp = (const float4*)(ssrow + (size_t)row * 16);
;         const float4 a = sp[0], b = sp[1], c = sp[2], d = sp[3];
;         const float ssum = (((a.x + a.y) + (a.z + a.w)) + ((b.x + b.y) + (b.z + b.w))) + (((c.x + c.y) + (c.z + c.w)) + ((d.x + d.y) + (d.z + d.w)));
;         const float rs = rsqrtf(ssum * (1.f / 1024.f) + 1e-6f);
; #pragma unroll
;         for (int bj = 0; bj < 2; ++bj) {
;           const int col = u.pn * 256 + bj * 128 + wc * 32 + fq * 8;
;           float h[8];
; #pragma unroll
;           for (int j = 0; j < 4; ++j) { const float h0 = fmaxf(acc[ai][bj][m][0][j] * rs, 0.f), h1 = fmaxf(acc[ai][bj][m][1][j] * rs, 0.f); h[j] = h0 * h0; h[4 + j] = h1 * h1; }
;           u32x4 w; w.x = pk2(h[0], h[1]); w.y = pk2(h[2], h[3]); w.z = pk2(h[4], h[5]); w.w = pk2(h[6], h[7]);
;           *(u32x4*)(uo + (size_t)row * DFF + col) = w;
;         }
	v_mov_b32_e32 v66, v184
	v_mov_b32_e32 v67, v185
	v_mov_b32_e32 v68, v186
	v_mov_b32_e32 v69, v187
	v_mov_b32_e32 v70, v188
	v_mov_b32_e32 v71, v189
	v_mov_b32_e32 v72, v190
	v_mov_b32_e32 v73, v191
	v_mov_b32_e32 v74, v192
	v_mov_b32_e32 v75, v193
	v_mov_b32_e32 v76, v194
	v_mov_b32_e32 v77, v195
	v_mov_b32_e32 v80, v196
	v_mov_b32_e32 v81, v197
	v_mov_b32_e32 v82, v198
	v_mov_b32_e32 v83, v199
	global_load_dwordx4 v[168:171], v[202:203], off offset:1072
	global_load_dwordx4 v[172:175], v[202:203], off offset:1040
	global_load_dwordx4 v[176:179], v[202:203], off offset:1056
	global_load_dwordx4 v[180:183], v[202:203], off offset:1024
	v_mov_b32_e32 v85, v74
	v_mov_b32_e32 v84, v80
	v_mov_b32_e32 v74, v81
	v_mov_b32_e32 v80, v82
	v_mov_b32_e32 v81, v76
	v_mov_b32_e32 v76, v83
	v_pk_add_f32 v[74:75], v[84:85], v[74:75]
	v_pk_add_f32 v[76:77], v[80:81], v[76:77]
	s_nop 0
	v_pk_add_f32 v[74:75], v[74:75], v[76:77]
	v_mov_b32_e32 v76, v70
	v_mov_b32_e32 v77, v66
	v_mov_b32_e32 v66, v71
	v_mov_b32_e32 v70, v72
	v_mov_b32_e32 v71, v68
	v_mov_b32_e32 v68, v73
	v_pk_add_f32 v[66:67], v[76:77], v[66:67]
	v_pk_add_f32 v[68:69], v[70:71], v[68:69]
	s_nop 0
	v_pk_add_f32 v[66:67], v[66:67], v[68:69]
	s_nop 0
	v_pk_add_f32 v[66:67], v[74:75], v[66:67]
	s_nop 0
	v_add_f32_e32 v66, v66, v67
	v_fmamk_f32 v66, v66, 0x3a800000, v224
	v_cmp_gt_f32_e32 vcc, s77, v66
	v_mul_f32_e32 v67, 0x4b800000, v66
	s_nop 0
	v_cndmask_b32_e32 v66, v66, v67, vcc
	v_rsq_f32_e32 v66, v66
	s_nop 0
	v_mul_f32_e32 v67, 0x45800000, v66
	v_cndmask_b32_e32 v68, v66, v67, vcc
	v_mul_f32_e32 v58, v58, v68
	v_mul_f32_e32 v59, v59, v68
	v_mul_f32_e32 v60, v60, v68
	v_max_f32_e32 v58, 0, v58
	v_max_f32_e32 v59, 0, v59
	v_max_f32_e32 v60, 0, v60
	v_mul_f32_e32 v62, v62, v68
	v_mul_f32_e32 v69, v58, v58
	v_mul_f32_e32 v58, v63, v68
	v_mul_f32_e32 v63, v59, v59
	v_mul_f32_e32 v59, v64, v68
	v_mul_f32_e32 v64, v60, v60
	v_mul_f32_e32 v60, v65, v68
	v_max_f32_e32 v62, 0, v62
	v_max_f32_e32 v58, 0, v58
	v_max_f32_e32 v59, 0, v59
	v_max_f32_e32 v60, 0, v60
	v_lshlrev_b64 v[66:67], 13, v[78:79]
	v_mul_f32_e32 v62, v62, v62
	v_mul_f32_e32 v58, v58, v58
	v_mul_f32_e32 v59, v59, v59
	v_mul_f32_e32 v61, v61, v68
	v_mul_f32_e32 v60, v60, v60
	v_max_f32_e32 v61, 0, v61
	v_cvt_pk_bf16_f32 v58, v62, v58
	v_cvt_pk_bf16_f32 v59, v59, v60
	v_cvt_pk_bf16_f32 v60, v69, v63
	v_lshl_add_u64 v[62:63], s[26:27], 0, v[66:67]
	v_mul_f32_e32 v50, v50, v68
	v_mul_f32_e32 v51, v51, v68
	v_mul_f32_e32 v52, v52, v68
	v_mul_f32_e32 v61, v61, v61
	v_lshl_add_u64 v[62:63], v[62:63], 0, v[126:127]
	v_max_f32_e32 v50, 0, v50
	v_max_f32_e32 v51, 0, v51
	v_max_f32_e32 v52, 0, v52
	v_cvt_pk_bf16_f32 v61, v64, v61
	global_store_dwordx4 v[62:63], v[58:61], off
	v_mul_f32_e32 v53, v53, v68
	v_mul_f32_e32 v54, v54, v68
	v_mul_f32_e32 v58, v50, v50
	v_mul_f32_e32 v50, v55, v68
	v_mul_f32_e32 v55, v51, v51
	v_mul_f32_e32 v51, v56, v68
	v_mul_f32_e32 v56, v52, v52
	v_mul_f32_e32 v52, v57, v68
	v_max_f32_e32 v50, 0, v50
	v_max_f32_e32 v51, 0, v51
	v_max_f32_e32 v52, 0, v52
	v_max_f32_e32 v53, 0, v53
	v_max_f32_e32 v54, 0, v54
	v_mul_f32_e32 v50, v50, v50
	v_mul_f32_e32 v51, v51, v51
	v_mul_f32_e32 v52, v52, v52
	v_mul_f32_e32 v53, v53, v53
	v_mul_f32_e32 v54, v54, v54
	v_cvt_pk_bf16_f32 v50, v54, v50
	v_cvt_pk_bf16_f32 v51, v51, v52
	v_cvt_pk_bf16_f32 v52, v58, v55
	v_cvt_pk_bf16_f32 v53, v56, v53
	global_store_dwordx4 v[62:63], v[50:53], off offset:256
	v_add_u32_e32 v62, 0x90, v146
	v_ashrrev_i32_e32 v63, 31, v62
	v_lshlrev_b64 v[50:51], 6, v[62:63]
	v_lshl_add_u64 v[64:65], s[54:55], 0, v[50:51]
	s_waitcnt vmcnt(2)
	v_mov_b32_e32 v50, v168
	v_mov_b32_e32 v51, v169
	v_mov_b32_e32 v52, v170
	v_mov_b32_e32 v53, v171
	v_mov_b32_e32 v54, v172
	v_mov_b32_e32 v55, v173
	v_mov_b32_e32 v56, v174
	v_mov_b32_e32 v57, v175
	v_mov_b32_e32 v58, v176
	v_mov_b32_e32 v59, v177
	v_mov_b32_e32 v60, v178
	v_mov_b32_e32 v61, v179
	v_mov_b32_e32 v64, v180
	v_mov_b32_e32 v65, v181
	v_mov_b32_e32 v66, v182
	v_mov_b32_e32 v67, v183
	global_load_dwordx4 v[184:187], v[202:203], off offset:2096
	global_load_dwordx4 v[188:191], v[202:203], off offset:2064
	global_load_dwordx4 v[192:195], v[202:203], off offset:2080
	global_load_dwordx4 v[196:199], v[202:203], off offset:2048
	v_mov_b32_e32 v69, v58
	v_mov_b32_e32 v68, v64
	v_mov_b32_e32 v58, v65
	v_mov_b32_e32 v64, v66
	v_mov_b32_e32 v65, v60
	v_mov_b32_e32 v60, v67
	v_pk_add_f32 v[58:59], v[68:69], v[58:59]
	v_pk_add_f32 v[60:61], v[64:65], v[60:61]
	s_nop 0
	v_pk_add_f32 v[58:59], v[58:59], v[60:61]
	v_mov_b32_e32 v60, v54
	v_mov_b32_e32 v61, v50
	v_mov_b32_e32 v50, v55
	v_mov_b32_e32 v54, v56
	v_mov_b32_e32 v55, v52
	v_mov_b32_e32 v52, v57
	v_pk_add_f32 v[50:51], v[60:61], v[50:51]
	v_pk_add_f32 v[52:53], v[54:55], v[52:53]
	s_nop 0
	v_pk_add_f32 v[50:51], v[50:51], v[52:53]
	s_nop 0
	v_pk_add_f32 v[50:51], v[58:59], v[50:51]
	s_nop 0
	v_add_f32_e32 v50, v50, v51
	v_fmamk_f32 v50, v50, 0x3a800000, v224
	v_cmp_gt_f32_e32 vcc, s77, v50
	v_mul_f32_e32 v51, 0x4b800000, v50
	s_nop 0
	v_cndmask_b32_e32 v50, v50, v51, vcc
	v_rsq_f32_e32 v50, v50
	s_nop 0
	v_mul_f32_e32 v51, 0x45800000, v50
	v_cndmask_b32_e32 v52, v50, v51, vcc
	v_mul_f32_e32 v42, v42, v52
	v_mul_f32_e32 v43, v43, v52
	v_mul_f32_e32 v44, v44, v52
	v_max_f32_e32 v42, 0, v42
	v_max_f32_e32 v43, 0, v43
	v_max_f32_e32 v44, 0, v44
	v_mul_f32_e32 v46, v46, v52
	v_mul_f32_e32 v53, v42, v42
	v_mul_f32_e32 v42, v47, v52
	v_mul_f32_e32 v47, v43, v43
	v_mul_f32_e32 v43, v48, v52
	v_mul_f32_e32 v48, v44, v44
	v_mul_f32_e32 v44, v49, v52
	v_max_f32_e32 v46, 0, v46
	v_max_f32_e32 v42, 0, v42
	v_max_f32_e32 v43, 0, v43
	v_max_f32_e32 v44, 0, v44
; DEVI unsigned pk2(float lo, float hi) { unsigned r; asm("v_cvt_pk_bf16_f32 %0, %1, %2" : "=v"(r) : "v"(lo), "v"(hi)); return r; }
;   DEVI void operator()(const f32x4 (&acc)[2][2][4][2], const pg8::Unit& u, int wr, int wc, int fr, int fq) const {
;     ...
;       for (int m = 0; m < 4; ++m) {
;         const int row = u.pm * 256 + ai * 128 + wr * 64 + m * 16 + fr;
;         const float4* sp = (const float4*)(ssrow + (size_t)row * 16);
;         const float4 a = sp[0], b = sp[1], c = sp[2], d = sp[3];
;         const float ssum = (((a.x + a.y) + (a.z + a.w)) + ((b.x + b.y) + (b.z + b.w))) + (((c.x + c.y) + (c.z + c.w)) + ((d.x + d.y) + (d.z + d.w)));
;         const float rs = rsqrtf(ssum * (1.f / 1024.f) + 1e-6f);
; #pragma unroll
;         for (int bj = 0; bj < 2; ++bj) {
;           const int col = u.pn * 256 + bj * 128 + wc * 32 + fq * 8;
;           float h[8];
; #pragma unroll
;           for (int j = 0; j < 4; ++j) { const float h0 = fmaxf(acc[ai][bj][m][0][j] * rs, 0.f), h1 = fmaxf(acc[ai][bj][m][1][j] * rs, 0.f); h[j] = h0 * h0; h[4 + j] = h1 * h1; }
;           u32x4 w; w.x = pk2(h[0], h[1]); w.y = pk2(h[2], h[3]); w.z = pk2(h[4], h[5]); w.w = pk2(h[6], h[7]);
;           *(u32x4*)(uo + (size_t)row * DFF + col) = w;
;         }
	v_lshlrev_b64 v[50:51], 13, v[62:63]
	v_mul_f32_e32 v46, v46, v46
	v_mul_f32_e32 v42, v42, v42
	v_mul_f32_e32 v43, v43, v43
	v_mul_f32_e32 v45, v45, v52
	v_mul_f32_e32 v44, v44, v44
	v_max_f32_e32 v45, 0, v45
	v_cvt_pk_bf16_f32 v42, v46, v42
	v_cvt_pk_bf16_f32 v43, v43, v44
	v_cvt_pk_bf16_f32 v44, v53, v47
	v_lshl_add_u64 v[46:47], s[26:27], 0, v[50:51]
	v_mul_f32_e32 v34, v34, v52
	v_mul_f32_e32 v35, v35, v52
	v_mul_f32_e32 v36, v36, v52
	v_mul_f32_e32 v45, v45, v45
	v_lshl_add_u64 v[46:47], v[46:47], 0, v[126:127]
	v_max_f32_e32 v34, 0, v34
	v_max_f32_e32 v35, 0, v35
	v_max_f32_e32 v36, 0, v36
	v_cvt_pk_bf16_f32 v45, v48, v45
	global_store_dwordx4 v[46:47], v[42:45], off
	v_mul_f32_e32 v37, v37, v52
	v_mul_f32_e32 v38, v38, v52
	v_mul_f32_e32 v42, v34, v34
	v_mul_f32_e32 v34, v39, v52
	v_mul_f32_e32 v39, v35, v35
	v_mul_f32_e32 v35, v40, v52
	v_mul_f32_e32 v40, v36, v36
	v_mul_f32_e32 v36, v41, v52
	v_max_f32_e32 v34, 0, v34
	v_max_f32_e32 v35, 0, v35
	v_max_f32_e32 v36, 0, v36
	v_max_f32_e32 v37, 0, v37
	v_max_f32_e32 v38, 0, v38
	v_mul_f32_e32 v34, v34, v34
	v_mul_f32_e32 v35, v35, v35
	v_mul_f32_e32 v36, v36, v36
	v_mul_f32_e32 v37, v37, v37
	v_mul_f32_e32 v38, v38, v38
	v_cvt_pk_bf16_f32 v34, v38, v34
	v_cvt_pk_bf16_f32 v35, v35, v36
	v_cvt_pk_bf16_f32 v36, v42, v39
	v_cvt_pk_bf16_f32 v37, v40, v37
	global_store_dwordx4 v[46:47], v[34:37], off offset:256
	v_add_u32_e32 v46, 0xa0, v146
	v_ashrrev_i32_e32 v47, 31, v46
	v_lshlrev_b64 v[34:35], 6, v[46:47]
	v_lshl_add_u64 v[48:49], s[54:55], 0, v[34:35]
	s_waitcnt vmcnt(2)
	v_mov_b32_e32 v34, v184
	v_mov_b32_e32 v35, v185
	v_mov_b32_e32 v36, v186
	v_mov_b32_e32 v37, v187
	v_mov_b32_e32 v38, v188
	v_mov_b32_e32 v39, v189
	v_mov_b32_e32 v40, v190
	v_mov_b32_e32 v41, v191
	v_mov_b32_e32 v42, v192
	v_mov_b32_e32 v43, v193
	v_mov_b32_e32 v44, v194
	v_mov_b32_e32 v45, v195
	v_mov_b32_e32 v48, v196
	v_mov_b32_e32 v49, v197
	v_mov_b32_e32 v50, v198
	v_mov_b32_e32 v51, v199
	global_load_dwordx4 v[168:171], v[202:203], off offset:3120
	global_load_dwordx4 v[172:175], v[202:203], off offset:3088
	global_load_dwordx4 v[176:179], v[202:203], off offset:3104
	global_load_dwordx4 v[180:183], v[202:203], off offset:3072
	v_mov_b32_e32 v53, v42
	v_mov_b32_e32 v52, v48
	v_mov_b32_e32 v42, v49
	v_mov_b32_e32 v48, v50
	v_mov_b32_e32 v49, v44
	v_mov_b32_e32 v44, v51
	v_pk_add_f32 v[42:43], v[52:53], v[42:43]
	v_pk_add_f32 v[44:45], v[48:49], v[44:45]
	s_nop 0
	v_pk_add_f32 v[42:43], v[42:43], v[44:45]
	v_mov_b32_e32 v44, v38
	v_mov_b32_e32 v45, v34
	v_mov_b32_e32 v34, v39
	v_mov_b32_e32 v38, v40
	v_mov_b32_e32 v39, v36
	v_mov_b32_e32 v36, v41
	v_pk_add_f32 v[34:35], v[44:45], v[34:35]
	v_pk_add_f32 v[36:37], v[38:39], v[36:37]
	s_nop 0
	v_pk_add_f32 v[34:35], v[34:35], v[36:37]
	s_nop 0
	v_pk_add_f32 v[34:35], v[42:43], v[34:35]
	s_nop 0
	v_add_f32_e32 v34, v34, v35
	v_fmamk_f32 v34, v34, 0x3a800000, v224
	v_cmp_gt_f32_e32 vcc, s77, v34
	v_mul_f32_e32 v35, 0x4b800000, v34
	s_nop 0
	v_cndmask_b32_e32 v34, v34, v35, vcc
	v_rsq_f32_e32 v34, v34
	s_nop 0
	v_mul_f32_e32 v35, 0x45800000, v34
	v_cndmask_b32_e32 v36, v34, v35, vcc
	v_mul_f32_e32 v24, v24, v36
	v_mul_f32_e32 v25, v25, v36
	v_mul_f32_e32 v26, v26, v36
	v_max_f32_e32 v24, 0, v24
	v_max_f32_e32 v25, 0, v25
	v_max_f32_e32 v26, 0, v26
	v_mul_f32_e32 v28, v28, v36
	v_mul_f32_e32 v37, v24, v24
	v_mul_f32_e32 v24, v29, v36
	v_mul_f32_e32 v29, v25, v25
	v_mul_f32_e32 v25, v30, v36
	v_mul_f32_e32 v30, v26, v26
	v_mul_f32_e32 v26, v31, v36
	v_max_f32_e32 v28, 0, v28
	v_max_f32_e32 v24, 0, v24
	v_max_f32_e32 v25, 0, v25
	v_max_f32_e32 v26, 0, v26
	v_lshlrev_b64 v[34:35], 13, v[46:47]
	v_mul_f32_e32 v28, v28, v28
	v_mul_f32_e32 v24, v24, v24
	v_mul_f32_e32 v25, v25, v25
	v_mul_f32_e32 v27, v27, v36
	v_mul_f32_e32 v26, v26, v26
	v_max_f32_e32 v27, 0, v27
	v_cvt_pk_bf16_f32 v24, v28, v24
	v_cvt_pk_bf16_f32 v25, v25, v26
	v_cvt_pk_bf16_f32 v26, v37, v29
	v_lshl_add_u64 v[28:29], s[26:27], 0, v[34:35]
	v_mul_f32_e32 v16, v16, v36
	v_mul_f32_e32 v17, v17, v36
	v_mul_f32_e32 v18, v18, v36
	v_mul_f32_e32 v27, v27, v27
	v_lshl_add_u64 v[28:29], v[28:29], 0, v[126:127]
	v_max_f32_e32 v16, 0, v16
	v_max_f32_e32 v17, 0, v17
	v_max_f32_e32 v18, 0, v18
	v_cvt_pk_bf16_f32 v27, v30, v27
	global_store_dwordx4 v[28:29], v[24:27], off
	v_mul_f32_e32 v19, v19, v36
	v_mul_f32_e32 v20, v20, v36
	v_mul_f32_e32 v24, v16, v16
	v_mul_f32_e32 v16, v21, v36
	v_mul_f32_e32 v21, v17, v17
	v_mul_f32_e32 v17, v22, v36
	v_mul_f32_e32 v22, v18, v18
	v_mul_f32_e32 v18, v23, v36
	v_max_f32_e32 v16, 0, v16
	v_max_f32_e32 v17, 0, v17
	v_max_f32_e32 v18, 0, v18
	v_max_f32_e32 v19, 0, v19
	v_max_f32_e32 v20, 0, v20
	v_mul_f32_e32 v16, v16, v16
	v_mul_f32_e32 v17, v17, v17
	v_mul_f32_e32 v18, v18, v18
	v_mul_f32_e32 v19, v19, v19
	v_mul_f32_e32 v20, v20, v20
	v_cvt_pk_bf16_f32 v16, v20, v16
	v_cvt_pk_bf16_f32 v17, v17, v18
	v_cvt_pk_bf16_f32 v18, v24, v21
	v_cvt_pk_bf16_f32 v19, v22, v19
	global_store_dwordx4 v[28:29], v[16:19], off offset:256
	v_add_u32_e32 v28, 0xb0, v146
	v_ashrrev_i32_e32 v29, 31, v28
	v_lshlrev_b64 v[16:17], 6, v[28:29]
	v_lshl_add_u64 v[30:31], s[54:55], 0, v[16:17]
	s_waitcnt vmcnt(2)
; DEVI unsigned pk2(float lo, float hi) { unsigned r; asm("v_cvt_pk_bf16_f32 %0, %1, %2" : "=v"(r) : "v"(lo), "v"(hi)); return r; }
;   DEVI void operator()(const f32x4 (&acc)[2][2][4][2], const pg8::Unit& u, int wr, int wc, int fr, int fq) const {
;     ...
;       for (int m = 0; m < 4; ++m) {
;         const int row = u.pm * 256 + ai * 128 + wr * 64 + m * 16 + fr;
;         const float4* sp = (const float4*)(ssrow + (size_t)row * 16);
;         const float4 a = sp[0], b = sp[1], c = sp[2], d = sp[3];
;         const float ssum = (((a.x + a.y) + (a.z + a.w)) + ((b.x + b.y) + (b.z + b.w))) + (((c.x + c.y) + (c.z + c.w)) + ((d.x + d.y) + (d.z + d.w)));
;         const float rs = rsqrtf(ssum * (1.f / 1024.f) + 1e-6f);
; #pragma unroll
;         for (int bj = 0; bj < 2; ++bj) {
;           const int col = u.pn * 256 + bj * 128 + wc * 32 + fq * 8;
;           float h[8];
; #pragma unroll
;           for (int j = 0; j < 4; ++j) { const float h0 = fmaxf(acc[ai][bj][m][0][j] * rs, 0.f), h1 = fmaxf(acc[ai][bj][m][1][j] * rs, 0.f); h[j] = h0 * h0; h[4 + j] = h1 * h1; }
;           u32x4 w; w.x = pk2(h[0], h[1]); w.y = pk2(h[2], h[3]); w.z = pk2(h[4], h[5]); w.w = pk2(h[6], h[7]);
;           *(u32x4*)(uo + (size_t)row * DFF + col) = w;
;         }
	v_mov_b32_e32 v16, v168
	v_mov_b32_e32 v17, v169
	v_mov_b32_e32 v18, v170
	v_mov_b32_e32 v19, v171
	v_mov_b32_e32 v20, v172
	v_mov_b32_e32 v21, v173
	v_mov_b32_e32 v22, v174
	v_mov_b32_e32 v23, v175
	v_mov_b32_e32 v24, v176
	v_mov_b32_e32 v25, v177
	v_mov_b32_e32 v26, v178
	v_mov_b32_e32 v27, v179
	v_mov_b32_e32 v34, v180
	v_mov_b32_e32 v35, v181
	v_mov_b32_e32 v36, v182
	v_mov_b32_e32 v37, v183
	v_mov_b32_e32 v31, v24
	v_mov_b32_e32 v30, v34
	v_mov_b32_e32 v24, v35
	v_pk_add_f32 v[24:25], v[30:31], v[24:25]
	v_mov_b32_e32 v30, v36
	v_mov_b32_e32 v31, v26
	v_mov_b32_e32 v26, v37
	v_pk_add_f32 v[26:27], v[30:31], v[26:27]
	s_nop 0
	v_pk_add_f32 v[24:25], v[24:25], v[26:27]
	v_mov_b32_e32 v26, v20
	v_mov_b32_e32 v27, v16
	v_mov_b32_e32 v16, v21
	v_mov_b32_e32 v20, v22
	v_mov_b32_e32 v21, v18
	v_mov_b32_e32 v18, v23
	v_pk_add_f32 v[16:17], v[26:27], v[16:17]
	v_pk_add_f32 v[18:19], v[20:21], v[18:19]
	s_nop 0
	v_pk_add_f32 v[16:17], v[16:17], v[18:19]
	s_nop 0
	v_pk_add_f32 v[16:17], v[24:25], v[16:17]
	s_nop 0
	v_add_f32_e32 v16, v16, v17
	v_fmamk_f32 v16, v16, 0x3a800000, v224
	v_cmp_gt_f32_e32 vcc, s77, v16
	v_mul_f32_e32 v17, 0x4b800000, v16
	s_nop 0
	v_cndmask_b32_e32 v16, v16, v17, vcc
	v_rsq_f32_e32 v16, v16
	s_nop 0
	v_mul_f32_e32 v17, 0x45800000, v16
	v_cndmask_b32_e32 v18, v16, v17, vcc
	v_mul_f32_e32 v8, v8, v18
	v_mul_f32_e32 v9, v9, v18
	v_mul_f32_e32 v10, v10, v18
	v_max_f32_e32 v8, 0, v8
	v_max_f32_e32 v9, 0, v9
	v_max_f32_e32 v10, 0, v10
	v_mul_f32_e32 v12, v12, v18
	v_mul_f32_e32 v19, v8, v8
	v_mul_f32_e32 v8, v13, v18
	v_mul_f32_e32 v13, v9, v9
	v_mul_f32_e32 v9, v14, v18
	v_mul_f32_e32 v14, v10, v10
	v_mul_f32_e32 v10, v15, v18
	v_max_f32_e32 v12, 0, v12
	v_max_f32_e32 v8, 0, v8
	v_max_f32_e32 v9, 0, v9
	v_max_f32_e32 v10, 0, v10
	v_lshlrev_b64 v[16:17], 13, v[28:29]
	v_mul_f32_e32 v12, v12, v12
	v_mul_f32_e32 v8, v8, v8
	v_mul_f32_e32 v9, v9, v9
	v_mul_f32_e32 v11, v11, v18
	v_mul_f32_e32 v10, v10, v10
	v_max_f32_e32 v11, 0, v11
	v_cvt_pk_bf16_f32 v8, v12, v8
	v_cvt_pk_bf16_f32 v9, v9, v10
	v_cvt_pk_bf16_f32 v10, v19, v13
	v_lshl_add_u64 v[12:13], s[26:27], 0, v[16:17]
	v_mul_f32_e32 v0, v0, v18
	v_mul_f32_e32 v1, v1, v18
	v_mul_f32_e32 v2, v2, v18
	v_mul_f32_e32 v11, v11, v11
	v_lshl_add_u64 v[12:13], v[12:13], 0, v[126:127]
	v_max_f32_e32 v0, 0, v0
	v_max_f32_e32 v1, 0, v1
	v_max_f32_e32 v2, 0, v2
	v_cvt_pk_bf16_f32 v11, v14, v11
	global_store_dwordx4 v[12:13], v[8:11], off
	v_mul_f32_e32 v3, v3, v18
	v_mul_f32_e32 v4, v4, v18
	v_mul_f32_e32 v8, v0, v0
	v_mul_f32_e32 v0, v5, v18
	v_mul_f32_e32 v5, v1, v1
	v_mul_f32_e32 v1, v6, v18
	v_mul_f32_e32 v6, v2, v2
	v_mul_f32_e32 v2, v7, v18
	v_max_f32_e32 v0, 0, v0
	v_max_f32_e32 v1, 0, v1
	v_max_f32_e32 v2, 0, v2
	v_max_f32_e32 v3, 0, v3
	v_max_f32_e32 v4, 0, v4
	v_mul_f32_e32 v0, v0, v0
	v_mul_f32_e32 v1, v1, v1
	v_mul_f32_e32 v2, v2, v2
	v_mul_f32_e32 v3, v3, v3
	s_andn2_b64 vcc, exec, s[4:5]
	v_mul_f32_e32 v4, v4, v4
	v_cvt_pk_bf16_f32 v0, v4, v0
	v_cvt_pk_bf16_f32 v1, v1, v2
	v_cvt_pk_bf16_f32 v2, v8, v5
	v_cvt_pk_bf16_f32 v3, v6, v3
	global_store_dwordx4 v[12:13], v[0:3], off offset:256
	s_cbranch_vccnz .LBB0_1963
	s_andn2_b64 vcc, exec, s[6:7]
	s_cbranch_vccnz .LBB0_1962
	s_barrier
	s_branch .LBB0_1962
